# combo8 + P1 shift/scale staging loop: all 17 partial loads and norm_g issued before the first wait (1 round trip per iteration instead of 2-3)
# baseline (speedup 1.0000x reference)
.LBB0_112:
	v_cmp_lt_u32_e32 vcc, s17, v7
	s_and_saveexec_b64 s[10:11], vcc
	v_lshl_add_u64 v[76:77], s[6:7], 0, v[4:5]
	global_load_dwordx4 v[72:75], v[76:77], off
	s_or_b64 exec, exec, s[10:11]
	v_lshl_add_u64 v[68:69], s[0:1], 0, v[4:5]
	v_add_co_u32_e32 v0, vcc, 0x1d000000, v68
	v_lshl_add_u64 v[44:45], s[42:43], 0, v[4:5]
	s_nop 0
	v_addc_co_u32_e32 v1, vcc, 0, v69, vcc
	v_add_co_u32_e32 v8, vcc, 0x1d030000, v68
	s_nop 1
	v_addc_co_u32_e32 v9, vcc, 0, v69, vcc
	v_add_co_u32_e32 v12, vcc, 0x1d060000, v68
	global_load_dwordx4 v[0:3], v[0:1], off
	s_nop 0
	global_load_dwordx4 v[8:11], v[8:9], off
	v_addc_co_u32_e32 v13, vcc, 0, v69, vcc
	v_add_co_u32_e32 v16, vcc, 0x1d090000, v68
	s_nop 1
	v_addc_co_u32_e32 v17, vcc, 0, v69, vcc
	v_add_co_u32_e32 v20, vcc, 0x1d0c0000, v68
	global_load_dwordx4 v[12:15], v[12:13], off
	s_nop 0
	global_load_dwordx4 v[16:19], v[16:17], off
	v_addc_co_u32_e32 v21, vcc, 0, v69, vcc
	v_add_co_u32_e32 v24, vcc, 0x1d0f0000, v68
	s_nop 1
	v_addc_co_u32_e32 v25, vcc, 0, v69, vcc
	v_add_co_u32_e32 v28, vcc, 0x1d120000, v68
	global_load_dwordx4 v[20:23], v[20:21], off
	s_nop 0
	global_load_dwordx4 v[24:27], v[24:25], off
	v_addc_co_u32_e32 v29, vcc, 0, v69, vcc
	v_add_co_u32_e32 v32, vcc, 0x1d150000, v68
	s_nop 1
	v_addc_co_u32_e32 v33, vcc, 0, v69, vcc
	v_add_co_u32_e32 v36, vcc, 0x1d180000, v68
	global_load_dwordx4 v[28:31], v[28:29], off
	s_nop 0
	global_load_dwordx4 v[32:35], v[32:33], off
	v_addc_co_u32_e32 v37, vcc, 0, v69, vcc
	v_add_co_u32_e32 v40, vcc, 0x1d1b0000, v68
	s_nop 1
	v_addc_co_u32_e32 v41, vcc, 0, v69, vcc
	global_load_dwordx4 v[36:39], v[36:37], off
	s_nop 0
	global_load_dwordx4 v[40:43], v[40:41], off
	v_add_co_u32_e32 v48, vcc, 0x1d1e0000, v68
	global_load_dwordx4 v[44:47], v[44:45], off
	s_nop 0
	v_addc_co_u32_e32 v49, vcc, 0, v69, vcc
	v_add_co_u32_e32 v52, vcc, 0x1d210000, v68
	s_nop 1
	v_addc_co_u32_e32 v53, vcc, 0, v69, vcc
	v_add_co_u32_e32 v56, vcc, 0x1d240000, v68
	global_load_dwordx4 v[48:51], v[48:49], off
	s_nop 0
	global_load_dwordx4 v[52:55], v[52:53], off
	v_addc_co_u32_e32 v57, vcc, 0, v69, vcc
	v_add_co_u32_e32 v60, vcc, 0x1d270000, v68
	s_nop 0
	s_nop 0
	v_addc_co_u32_e32 v61, vcc, 0, v69, vcc
	v_add_co_u32_e32 v64, vcc, 0x1d2a0000, v68
	global_load_dwordx4 v[56:59], v[56:57], off
	s_nop 0
	global_load_dwordx4 v[60:63], v[60:61], off
	v_addc_co_u32_e32 v65, vcc, 0, v69, vcc
	v_add_co_u32_e32 v68, vcc, 0x1d2d0000, v68
	global_load_dwordx4 v[64:67], v[64:65], off
	s_nop 0
	v_addc_co_u32_e32 v69, vcc, 0, v69, vcc
	global_load_dwordx4 v[68:71], v[68:69], off
	s_waitcnt vmcnt(6)
	v_pk_add_f32 v[2:3], v[46:47], v[2:3]
	v_pk_add_f32 v[0:1], v[44:45], v[0:1]
	v_pk_add_f32 v[2:3], v[2:3], v[10:11]
	v_pk_add_f32 v[0:1], v[0:1], v[8:9]
	v_pk_add_f32 v[2:3], v[2:3], v[14:15]
	v_pk_add_f32 v[0:1], v[0:1], v[12:13]
	v_pk_add_f32 v[2:3], v[2:3], v[18:19]
	v_pk_add_f32 v[0:1], v[0:1], v[16:17]
	v_pk_add_f32 v[2:3], v[2:3], v[22:23]
	v_pk_add_f32 v[0:1], v[0:1], v[20:21]
	v_pk_add_f32 v[2:3], v[2:3], v[26:27]
	v_pk_add_f32 v[0:1], v[0:1], v[24:25]
	v_pk_add_f32 v[2:3], v[2:3], v[30:31]
	v_pk_add_f32 v[0:1], v[0:1], v[28:29]
	v_pk_add_f32 v[2:3], v[2:3], v[34:35]
	v_pk_add_f32 v[0:1], v[0:1], v[32:33]
	v_pk_add_f32 v[2:3], v[2:3], v[38:39]
	v_pk_add_f32 v[0:1], v[0:1], v[36:37]
	v_pk_add_f32 v[2:3], v[2:3], v[42:43]
	v_pk_add_f32 v[0:1], v[0:1], v[40:41]
	v_cmp_lt_u32_e32 vcc, s17, v7
	s_waitcnt vmcnt(5)
	v_pk_add_f32 v[2:3], v[2:3], v[50:51]
	v_pk_add_f32 v[0:1], v[0:1], v[48:49]
	s_waitcnt vmcnt(4)
	v_pk_add_f32 v[2:3], v[2:3], v[54:55]
	v_pk_add_f32 v[0:1], v[0:1], v[52:53]
	s_waitcnt vmcnt(3)
	v_pk_add_f32 v[2:3], v[2:3], v[58:59]
	v_pk_add_f32 v[0:1], v[0:1], v[56:57]
	s_waitcnt vmcnt(2)
	v_pk_add_f32 v[2:3], v[2:3], v[62:63]
	v_pk_add_f32 v[0:1], v[0:1], v[60:61]
	s_waitcnt vmcnt(1)
	v_pk_add_f32 v[2:3], v[2:3], v[66:67]
	v_pk_add_f32 v[0:1], v[0:1], v[64:65]
	s_waitcnt vmcnt(0)
	v_pk_add_f32 v[2:3], v[2:3], v[70:71]
	v_pk_add_f32 v[0:1], v[0:1], v[68:69]
	s_and_saveexec_b64 s[10:11], vcc
	s_cbranch_execz .LBB0_111
	v_pk_add_f32 v[2:3], v[2:3], 1.0 op_sel_hi:[1,0]
	v_pk_add_f32 v[0:1], v[0:1], 1.0 op_sel_hi:[1,0]
	s_waitcnt vmcnt(0)
	v_pk_mul_f32 v[2:3], v[2:3], v[74:75]
	v_pk_mul_f32 v[0:1], v[0:1], v[72:73]
	s_branch .LBB0_111
